# P2 global queue order: sample retention/attention items before the long MODE-0 retention segments so their flag wait overlaps useful work
# speedup vs baseline: 1.0114x; 1.0015x over previous
; __device__ __forceinline__ int fresh_tid(int wave_s) { unsigned m = ~0u; asm volatile("" : "+s"(m)); int t = wave_s * 64 + (int)__builtin_amdgcn_mbcnt_hi(m, __builtin_amdgcn_mbcnt_lo(m, 0u)); asm volatile("" : "+v"(t)); return t; }
; __global__ void __launch_bounds__(512, 2) hybrid_fwd(Ctx c) {
;     ...
;         for (;;) {
;             if (fresh_tid(wave0) == 0) MISC[16] = atomicAdd(ctl + CW_QUEUE, 1u);
;             __syncthreads();
;             const int it = (int)MISC[16];
;             __syncthreads();
;             if (it >= 432) break;
;             if (it < 112) { const int bh = it / 7, sg = it % 7; ret_unit<2>(c, lds, bh >> 2, bh & 3, sg, wave0); }
;             else if (it < 240) { const int k = it - 112, bh = k >> 3, sg = k & 7; ret_unit<0>(c, lds, bh >> 2, bh & 3, sg, wave0); }
;             else if (it < 304) ret_unit<1>(c, lds, (it - 240) >> 2, (it - 240) & 3, 0, wave0);
;             else attn_unit16<true>(c, lds, (it - 304) >> 3, (it - 304) & 7, 0, wave0);
.LBB0_663:
	s_or_b64 exec, exec, s[0:1]
	s_waitcnt lgkmcnt(0)
	s_barrier
	ds_read_b32 v0, v216
	s_movk_i32 s0, 0x1af
	s_waitcnt lgkmcnt(0)
	s_barrier
	v_cmp_lt_i32_e32 vcc, s0, v0
	v_readfirstlane_b32 s58, v0
	s_mov_b64 s[0:1], -1
	s_cbranch_vccnz .LBB0_658
	s_cmpk_gt_u32 s58, 0x6f
	s_cselect_b32 s99, 0x80, 0
	s_cmpk_gt_u32 s58, 0x12f
	s_cselect_b32 s99, 0xffffff40, s99
	s_add_i32 s58, s58, s99
	s_cmpk_gt_i32 s58, 0x6f
	s_cbranch_scc0 .LBB0_806
	s_cmpk_gt_u32 s58, 0xef
	s_cbranch_scc0 .LBB0_756
	s_cmpk_gt_u32 s58, 0x12f
	s_cbranch_scc0 .LBB0_744
	s_and_b32 s0, s58, 7
	s_mov_b32 s1, -1
	s_nop 0
	v_mbcnt_lo_u32_b32 v0, s1, 0
	v_mbcnt_hi_u32_b32 v0, s1, v0
	v_add_u32_e32 v24, s33, v0
	s_movk_i32 s1, 0xff
	s_nop 0
	v_readfirstlane_b32 s12, v24
	v_cmp_lt_i32_e32 vcc, s1, v24
	s_and_saveexec_b64 s[2:3], vcc
	s_xor_b64 s[2:3], exec, s[2:3]
	s_mov_b32 s1, s75
	s_or_saveexec_b64 s[2:3], s[2:3]
	v_mov_b64_e32 v[18:19], s[0:1]
	s_xor_b64 exec, exec, s[2:3]
	s_cbranch_execz .LBB0_679
	v_add_u32_e32 v0, 0xffffff80, v24
	v_sub_u32_e32 v2, 0x80, v24
	v_max_i32_e32 v0, v0, v2
	v_cmp_lt_u32_e32 vcc, 7, v0
	s_and_saveexec_b64 s[4:5], vcc
	s_cbranch_execz .LBB0_678
	v_cmp_lt_u32_e32 vcc, 11, v0
	v_mov_b32_e32 v2, 8
	s_and_saveexec_b64 s[6:7], vcc
	s_cbranch_execz .LBB0_677
	v_cmp_lt_u32_e32 vcc, 15, v0
	v_mov_b32_e32 v2, 9
	s_and_saveexec_b64 s[8:9], vcc
	s_cbranch_execz .LBB0_676
	v_cmp_lt_u32_e32 vcc, 22, v0
	v_mov_b32_e32 v2, 10
	s_and_saveexec_b64 s[10:11], vcc
	s_movk_i32 s1, 0x5b
	v_cmp_gt_u32_e32 vcc, s1, v0
	s_nop 1
	v_cndmask_b32_e64 v2, 15, 14, vcc
	v_cmp_lt_u32_e32 vcc, 63, v0
	s_nop 1
	v_cndmask_b32_e32 v2, 13, v2, vcc
	v_cmp_lt_u32_e32 vcc, 45, v0
	s_nop 1
	v_cndmask_b32_e32 v2, 12, v2, vcc
	v_cmp_lt_u32_e32 vcc, 31, v0
	s_nop 1
	v_cndmask_b32_e32 v2, 11, v2, vcc
	s_or_b64 exec, exec, s[10:11]
